# v21: v17 with tighter generation-word polling (s_sleep 0) in the grid barrier waiters
# speedup vs baseline: 1.0034x; 1.0034x over previous
.Lxb0_wait:
	global_load_dword v248, v253, s[60:61] sc1
	v_add_u32_e32 v252, 1, v252
	s_waitcnt vmcnt(0)
	v_cmp_ge_u32_e32 vcc, v248, v249
	s_cbranch_vccnz .Lxb0_wdone
	v_cmp_gt_u32_e32 vcc, 0x100000, v252
	s_cbranch_vccz .Lxb0_wdone
	s_sleep 0
	s_branch .Lxb0_wait
